# P7 tile loops: next tile's LDS-DMA issue (SALU address math + 8 DMAs) moved behind the QK^T MFMA issue; skipped tiles issue it on a side path
# baseline (speedup 1.0000x reference)
.LBB0_734:
	s_sub_i32 s7, s72, 63
	s_cmp_gt_u32 s7, s3
	s_cbranch_scc1 .Lp7dma_skip0
	v_add_u32_e32 v1, s6, v222
	v_add_u32_e32 v2, v1, v225
	ds_read_b128 v[4:7], v2
	ds_read_b128 v[8:11], v2 offset:8192
	v_add_u32_e32 v2, v1, v224
	ds_read_b128 v[12:15], v2 offset:8192
	ds_read_b128 v[146:149], v2
	v_add_u32_e32 v2, s6, v233
	s_waitcnt lgkmcnt(0)
	v_mfma_f32_32x32x16_bf16 v[162:177], v[146:149], v[178:181], 0
	v_mfma_f32_32x32x16_bf16 v[146:161], v[12:15], v[178:181], 0
	v_add_u32_e32 v16, v1, v226
	ds_read_b128 v[12:15], v16
	ds_read_b128 v[238:241], v16 offset:8192
	v_mfma_f32_32x32x16_bf16 v[162:177], v[4:7], v[182:185], v[162:177]
	v_mfma_f32_32x32x16_bf16 v[146:161], v[8:11], v[182:185], v[146:161]
	v_add_u32_e32 v8, v1, v227
	ds_read_b128 v[4:7], v8
	ds_read_b128 v[8:11], v8 offset:8192
	s_waitcnt lgkmcnt(3)
	v_mfma_f32_32x32x16_bf16 v[162:177], v[12:15], v[186:189], v[162:177]
	s_waitcnt lgkmcnt(2)
	v_mfma_f32_32x32x16_bf16 v[146:161], v[238:241], v[186:189], v[146:161]
	v_add_u32_e32 v16, v1, v228
	ds_read_b128 v[12:15], v16
	ds_read_b128 v[238:241], v16 offset:8192
	s_waitcnt lgkmcnt(3)
	v_mfma_f32_32x32x16_bf16 v[162:177], v[4:7], v[190:193], v[162:177]
	s_waitcnt lgkmcnt(2)
	v_mfma_f32_32x32x16_bf16 v[146:161], v[8:11], v[190:193], v[146:161]
	v_add_u32_e32 v8, v1, v229
	ds_read_b128 v[4:7], v8
	ds_read_b128 v[8:11], v8 offset:8192
	s_waitcnt lgkmcnt(3)
	v_mfma_f32_32x32x16_bf16 v[162:177], v[12:15], v[194:197], v[162:177]
	s_waitcnt lgkmcnt(2)
	v_mfma_f32_32x32x16_bf16 v[146:161], v[238:241], v[194:197], v[146:161]
	v_add_u32_e32 v16, v1, v230
	ds_read_b128 v[12:15], v16
	ds_read_b128 v[238:241], v16 offset:8192
	s_waitcnt lgkmcnt(3)
	v_mfma_f32_32x32x16_bf16 v[162:177], v[4:7], v[198:201], v[162:177]
	s_waitcnt lgkmcnt(2)
	v_mfma_f32_32x32x16_bf16 v[146:161], v[8:11], v[198:201], v[146:161]
	v_add_u32_e32 v1, v1, v231
	ds_read_b128 v[4:7], v1
	ds_read_b128 v[8:11], v1 offset:8192
	s_waitcnt lgkmcnt(3)
	v_mfma_f32_32x32x16_bf16 v[162:177], v[12:15], v[202:205], v[162:177]
	s_waitcnt lgkmcnt(2)
	v_mfma_f32_32x32x16_bf16 v[146:161], v[238:241], v[202:205], v[146:161]
	s_waitcnt lgkmcnt(1)
	v_mfma_f32_32x32x16_bf16 v[162:177], v[4:7], v[206:209], v[162:177]
	s_waitcnt lgkmcnt(0)
	v_mfma_f32_32x32x16_bf16 v[146:161], v[8:11], v[206:209], v[146:161]
	ds_read_b64_tr_b16 v[8:9], v2 offset:0
	ds_read_b64_tr_b16 v[10:11], v2 offset:0x1000
	ds_read_b64_tr_b16 v[4:5], v2 offset:0x2000
	ds_read_b64_tr_b16 v[6:7], v2 offset:0x3000
	s_add_i32 s7, s76, 3
	s_cmp_ge_u32 s7, s74
	s_cbranch_scc1 .Lp7dma_none0
	s_lshr_b32 s7, s7, 2
	s_and_b32 s8, s75, 0xc000
	s_mul_hi_u32 s9, s7, 0x180000
	s_mul_i32 s7, s7, 0x180000
	s_or_b32 s8, s7, s8
	s_lshl_b64 s[8:9], s[8:9], 1
	s_add_u32 s10, s94, s8
	s_addc_u32 s11, s95, s9
	s_add_u32 s12, s88, s8
	s_addc_u32 s13, s89, s9
	s_add_u32 s8, s90, s8
	s_addc_u32 s9, s91, s9
	s_sub_i32 s7, s70, s6
	s_mov_b32 s14, m0
	s_mov_b32 m0, s7
	s_nop 0
	global_load_lds_dwordx4 v243, s[10:11]
	s_add_u32 m0, m0, 0x2000
	s_nop 0
	global_load_lds_dwordx4 v244, s[10:11]
	s_add_u32 m0, m0, 0x2000
	s_nop 0
	global_load_lds_dwordx4 v243, s[12:13]
	s_add_u32 m0, m0, 0x2000
	s_nop 0
	global_load_lds_dwordx4 v244, s[12:13]
	s_add_u32 m0, m0, 0x2000
	s_nop 0
	global_load_lds_dwordx4 v245, s[8:9]
	s_add_u32 m0, m0, 0x2000
	s_nop 0
	global_load_lds_dwordx4 v246, s[8:9]
	s_add_u32 m0, m0, 0x2000
	s_nop 0
	global_load_lds_dwordx4 v247, s[8:9]
	s_add_u32 m0, m0, 0x2000
	s_nop 0
	global_load_lds_dwordx4 v248, s[8:9]
	s_mov_b32 m0, s14
.Lp7dma_none0:
	s_cmp_le_u32 s72, s1
	s_cbranch_scc1 .LBB0_737
	v_cmp_gt_i32_e64 s[66:67], 26, v234
	v_cmp_gt_i32_e64 s[68:69], 27, v234
	v_cmp_gt_i32_e64 s[64:65], 25, v234
	s_and_b64 s[66:67], s[68:69], s[66:67]
	v_cmp_gt_i32_e64 s[62:63], 24, v234
	s_and_b64 s[64:65], s[66:67], s[64:65]
	v_cmp_gt_i32_e64 s[60:61], 19, v234
	s_and_b64 s[62:63], s[64:65], s[62:63]
	v_cmp_gt_i32_e64 s[58:59], 18, v234
	s_and_b64 s[60:61], s[62:63], s[60:61]
	v_cmp_gt_i32_e64 s[56:57], 17, v234
	s_and_b64 s[58:59], s[60:61], s[58:59]
	v_cmp_gt_i32_e64 s[54:55], 16, v234
	s_and_b64 s[56:57], s[58:59], s[56:57]
	v_cmp_gt_i32_e64 s[52:53], 11, v234
	s_and_b64 s[54:55], s[56:57], s[54:55]
	v_cmp_gt_i32_e64 s[50:51], 10, v234
	s_and_b64 s[52:53], s[54:55], s[52:53]
	v_cmp_gt_i32_e64 s[48:49], 9, v234
	s_and_b64 s[50:51], s[52:53], s[50:51]
	v_cmp_gt_i32_e64 s[46:47], 8, v234
	s_and_b64 s[48:49], s[50:51], s[48:49]
	v_cmp_gt_i32_e64 s[44:45], 3, v234
	s_and_b64 s[46:47], s[48:49], s[46:47]
	v_cmp_gt_i32_e64 s[42:43], 2, v234
	s_and_b64 s[44:45], s[46:47], s[44:45]
	v_cmp_gt_i32_e64 s[40:41], 1, v234
	s_and_b64 s[42:43], s[44:45], s[42:43]
	v_cmp_gt_i32_e64 s[38:39], 0, v234
	s_and_b64 s[40:41], s[42:43], s[40:41]
	s_and_b64 s[38:39], s[40:41], s[38:39]
	v_cmp_gt_i32_e64 s[34:35], 58, v234
	v_cndmask_b32_e64 v162, v162, v215, s[38:39]
	v_cmp_gt_i32_e64 s[38:39], 59, v234
	v_cmp_gt_i32_e64 s[30:31], 57, v234
	s_and_b64 s[34:35], s[38:39], s[34:35]
	v_cmp_gt_i32_e64 s[28:29], 56, v234
	s_and_b64 s[30:31], s[34:35], s[30:31]
	v_cmp_gt_i32_e64 s[26:27], 51, v234
	s_and_b64 s[28:29], s[30:31], s[28:29]
	v_cmp_gt_i32_e64 s[24:25], 50, v234
	s_and_b64 s[26:27], s[28:29], s[26:27]
	v_cmp_gt_i32_e64 s[22:23], 49, v234
	s_and_b64 s[24:25], s[26:27], s[24:25]
	v_cmp_gt_i32_e64 s[20:21], 48, v234
	s_and_b64 s[22:23], s[24:25], s[22:23]
	v_cmp_gt_i32_e64 s[18:19], 43, v234
	s_and_b64 s[20:21], s[22:23], s[20:21]
	v_cmp_gt_i32_e64 s[16:17], 42, v234
	s_and_b64 s[18:19], s[20:21], s[18:19]
	v_cmp_gt_i32_e64 s[14:15], 41, v234
	s_and_b64 s[16:17], s[18:19], s[16:17]
	v_cmp_gt_i32_e64 s[12:13], 40, v234
	s_and_b64 s[14:15], s[16:17], s[14:15]
	v_cmp_gt_i32_e64 s[10:11], 35, v234
	s_and_b64 s[12:13], s[14:15], s[12:13]
	v_cmp_gt_i32_e64 s[8:9], 34, v234
	s_and_b64 s[10:11], s[12:13], s[10:11]
	v_cmp_gt_i32_e64 s[6:7], 33, v234
	s_and_b64 s[8:9], s[10:11], s[8:9]
	v_cmp_gt_i32_e32 vcc, 32, v234
	s_and_b64 s[6:7], s[8:9], s[6:7]
	s_and_b64 vcc, s[6:7], vcc
	v_cndmask_b32_e64 v177, v177, v215, s[68:69]
	v_cndmask_b32_e64 v176, v176, v215, s[66:67]
	v_cndmask_b32_e64 v175, v175, v215, s[64:65]
	v_cndmask_b32_e64 v174, v174, v215, s[62:63]
	v_cndmask_b32_e64 v173, v173, v215, s[60:61]
	v_cndmask_b32_e64 v172, v172, v215, s[58:59]
	v_cndmask_b32_e64 v171, v171, v215, s[56:57]
	v_cndmask_b32_e64 v170, v170, v215, s[54:55]
	v_cndmask_b32_e64 v169, v169, v215, s[52:53]
	v_cndmask_b32_e64 v168, v168, v215, s[50:51]
	v_cndmask_b32_e64 v167, v167, v215, s[48:49]
	v_cndmask_b32_e64 v166, v166, v215, s[46:47]
	v_cndmask_b32_e64 v165, v165, v215, s[44:45]
	v_cndmask_b32_e64 v164, v164, v215, s[42:43]
	v_cndmask_b32_e64 v163, v163, v215, s[40:41]
	v_cndmask_b32_e64 v161, v161, v215, s[38:39]
	v_cndmask_b32_e64 v160, v160, v215, s[34:35]
	v_cndmask_b32_e64 v159, v159, v215, s[30:31]
	v_cndmask_b32_e64 v158, v158, v215, s[28:29]
	v_cndmask_b32_e64 v157, v157, v215, s[26:27]
	v_cndmask_b32_e64 v156, v156, v215, s[24:25]
	v_cndmask_b32_e64 v155, v155, v215, s[22:23]
	v_cndmask_b32_e64 v154, v154, v215, s[20:21]
	v_cndmask_b32_e64 v153, v153, v215, s[18:19]
	v_cndmask_b32_e64 v152, v152, v215, s[16:17]
	v_cndmask_b32_e64 v151, v151, v215, s[14:15]
	v_cndmask_b32_e64 v150, v150, v215, s[12:13]
	v_cndmask_b32_e64 v149, v149, v215, s[10:11]
	v_cndmask_b32_e64 v148, v148, v215, s[8:9]
	v_cndmask_b32_e64 v147, v147, v215, s[6:7]
	v_cndmask_b32_e32 v146, v146, v215, vcc

.Lp7dma_skip0:
	s_add_i32 s7, s76, 3
	s_cmp_ge_u32 s7, s74
	s_cbranch_scc1 .LBB0_731
	s_lshr_b32 s7, s7, 2
	s_and_b32 s8, s75, 0xc000
	s_mul_hi_u32 s9, s7, 0x180000
	s_mul_i32 s7, s7, 0x180000
	s_or_b32 s8, s7, s8
	s_lshl_b64 s[8:9], s[8:9], 1
	s_add_u32 s10, s94, s8
	s_addc_u32 s11, s95, s9
	s_add_u32 s12, s88, s8
	s_addc_u32 s13, s89, s9
	s_add_u32 s8, s90, s8
	s_addc_u32 s9, s91, s9
	s_sub_i32 s7, s70, s6
	s_mov_b32 s14, m0
	s_mov_b32 m0, s7
	s_nop 0
	global_load_lds_dwordx4 v243, s[10:11]
	s_add_u32 m0, m0, 0x2000
	s_nop 0
	global_load_lds_dwordx4 v244, s[10:11]
	s_add_u32 m0, m0, 0x2000
	s_nop 0
	global_load_lds_dwordx4 v243, s[12:13]
	s_add_u32 m0, m0, 0x2000
	s_nop 0
	global_load_lds_dwordx4 v244, s[12:13]
	s_add_u32 m0, m0, 0x2000
	s_nop 0
	global_load_lds_dwordx4 v245, s[8:9]
	s_add_u32 m0, m0, 0x2000
	s_nop 0
	global_load_lds_dwordx4 v246, s[8:9]
	s_add_u32 m0, m0, 0x2000
	s_nop 0
	global_load_lds_dwordx4 v247, s[8:9]
	s_add_u32 m0, m0, 0x2000
	s_nop 0
	global_load_lds_dwordx4 v248, s[8:9]
	s_mov_b32 m0, s14
	s_branch .LBB0_731

.LBB0_755:
	s_cmp_gt_i32 s0, s3
	s_cbranch_scc1 .Lp7dma_skip1
	v_add_u32_e32 v1, s6, v222
	v_add_u32_e32 v2, v1, v224
	ds_read_b128 v[4:7], v2
	ds_read_b128 v[8:11], v2 offset:8192
	v_add_u32_e32 v2, v1, v223
	ds_read_b128 v[12:15], v2 offset:8192
	ds_read_b128 v[146:149], v2
	v_add_u32_e32 v2, s6, v233
	s_waitcnt lgkmcnt(0)
	v_mfma_f32_32x32x16_bf16 v[162:177], v[146:149], v[178:181], 0
	v_mfma_f32_32x32x16_bf16 v[146:161], v[12:15], v[178:181], 0
	v_add_u32_e32 v16, v1, v225
	ds_read_b128 v[12:15], v16
	ds_read_b128 v[238:241], v16 offset:8192
	v_mfma_f32_32x32x16_bf16 v[162:177], v[4:7], v[182:185], v[162:177]
	v_mfma_f32_32x32x16_bf16 v[146:161], v[8:11], v[182:185], v[146:161]
	v_add_u32_e32 v8, v1, v226
	ds_read_b128 v[4:7], v8
	ds_read_b128 v[8:11], v8 offset:8192
	s_waitcnt lgkmcnt(3)
	v_mfma_f32_32x32x16_bf16 v[162:177], v[12:15], v[186:189], v[162:177]
	s_waitcnt lgkmcnt(2)
	v_mfma_f32_32x32x16_bf16 v[146:161], v[238:241], v[186:189], v[146:161]
	v_add_u32_e32 v16, v1, v227
	ds_read_b128 v[12:15], v16
	ds_read_b128 v[238:241], v16 offset:8192
	s_waitcnt lgkmcnt(3)
	v_mfma_f32_32x32x16_bf16 v[162:177], v[4:7], v[190:193], v[162:177]
	s_waitcnt lgkmcnt(2)
	v_mfma_f32_32x32x16_bf16 v[146:161], v[8:11], v[190:193], v[146:161]
	v_add_u32_e32 v8, v1, v229
	ds_read_b128 v[4:7], v8
	ds_read_b128 v[8:11], v8 offset:8192
	s_waitcnt lgkmcnt(3)
	v_mfma_f32_32x32x16_bf16 v[162:177], v[12:15], v[194:197], v[162:177]
	s_waitcnt lgkmcnt(2)
	v_mfma_f32_32x32x16_bf16 v[146:161], v[238:241], v[194:197], v[146:161]
	v_add_u32_e32 v16, v1, v230
	ds_read_b128 v[12:15], v16
	ds_read_b128 v[238:241], v16 offset:8192
	s_waitcnt lgkmcnt(3)
	v_mfma_f32_32x32x16_bf16 v[162:177], v[4:7], v[198:201], v[162:177]
	s_waitcnt lgkmcnt(2)
	v_mfma_f32_32x32x16_bf16 v[146:161], v[8:11], v[198:201], v[146:161]
	v_add_u32_e32 v1, v1, v231
	ds_read_b128 v[4:7], v1
	ds_read_b128 v[8:11], v1 offset:8192
	s_waitcnt lgkmcnt(3)
	v_mfma_f32_32x32x16_bf16 v[162:177], v[12:15], v[202:205], v[162:177]
	s_waitcnt lgkmcnt(2)
	v_mfma_f32_32x32x16_bf16 v[146:161], v[238:241], v[202:205], v[146:161]
	s_waitcnt lgkmcnt(1)
	v_mfma_f32_32x32x16_bf16 v[162:177], v[4:7], v[206:209], v[162:177]
	s_waitcnt lgkmcnt(0)
	v_mfma_f32_32x32x16_bf16 v[146:161], v[8:11], v[206:209], v[146:161]
	ds_read_b64_tr_b16 v[8:9], v2 offset:0
	ds_read_b64_tr_b16 v[10:11], v2 offset:0x1000
	ds_read_b64_tr_b16 v[4:5], v2 offset:0x2000
	ds_read_b64_tr_b16 v[6:7], v2 offset:0x3000
	s_cmp_ge_u32 s71, s95
	s_cbranch_scc1 .Lp7dma_none1
	s_ashr_i32 s7, s88, 2
	s_and_b32 s8, s1, 0xc000
	s_mul_hi_i32 s9, s7, 0x180000
	s_mul_i32 s7, s7, 0x180000
	s_or_b32 s8, s7, s8
	s_lshl_b64 s[8:9], s[8:9], 1
	s_add_u32 s10, s89, s8
	s_addc_u32 s11, s90, s9
	s_add_u32 s12, s74, s8
	s_addc_u32 s13, s75, s9
	s_add_u32 s8, s91, s8
	s_addc_u32 s9, s94, s9
	s_sub_i32 s7, s70, s6
	s_mov_b32 s14, m0
	s_mov_b32 m0, s7
	s_nop 0
	global_load_lds_dwordx4 v243, s[10:11]
	s_add_u32 m0, m0, 0x2000
	s_nop 0
	global_load_lds_dwordx4 v244, s[10:11]
	s_add_u32 m0, m0, 0x2000
	s_nop 0
	global_load_lds_dwordx4 v243, s[12:13]
	s_add_u32 m0, m0, 0x2000
	s_nop 0
	global_load_lds_dwordx4 v244, s[12:13]
	s_add_u32 m0, m0, 0x2000
	s_nop 0
	global_load_lds_dwordx4 v245, s[8:9]
	s_add_u32 m0, m0, 0x2000
	s_nop 0
	global_load_lds_dwordx4 v246, s[8:9]
	s_add_u32 m0, m0, 0x2000
	s_nop 0
	global_load_lds_dwordx4 v247, s[8:9]
	s_add_u32 m0, m0, 0x2000
	s_nop 0
	global_load_lds_dwordx4 v248, s[8:9]
	s_mov_b32 m0, s14
.Lp7dma_none1:
	s_add_i32 s6, s0, 63
	s_cmp_le_i32 s6, s76
	s_cbranch_scc1 .LBB0_758
	v_cmp_gt_i32_e64 s[66:67], 26, v234
	v_cmp_gt_i32_e64 s[68:69], 27, v234
	v_cmp_gt_i32_e64 s[64:65], 25, v234
	s_and_b64 s[66:67], s[68:69], s[66:67]
	v_cmp_gt_i32_e64 s[62:63], 24, v234
	s_and_b64 s[64:65], s[66:67], s[64:65]
	v_cmp_gt_i32_e64 s[60:61], 19, v234
	s_and_b64 s[62:63], s[64:65], s[62:63]
	v_cmp_gt_i32_e64 s[58:59], 18, v234
	s_and_b64 s[60:61], s[62:63], s[60:61]
	v_cmp_gt_i32_e64 s[56:57], 17, v234
	s_and_b64 s[58:59], s[60:61], s[58:59]
	v_cmp_gt_i32_e64 s[54:55], 16, v234
	s_and_b64 s[56:57], s[58:59], s[56:57]
	v_cmp_gt_i32_e64 s[52:53], 11, v234
	s_and_b64 s[54:55], s[56:57], s[54:55]
	v_cmp_gt_i32_e64 s[50:51], 10, v234
	s_and_b64 s[52:53], s[54:55], s[52:53]
	v_cmp_gt_i32_e64 s[48:49], 9, v234
	s_and_b64 s[50:51], s[52:53], s[50:51]
	v_cmp_gt_i32_e64 s[46:47], 8, v234
	s_and_b64 s[48:49], s[50:51], s[48:49]
	v_cmp_gt_i32_e64 s[44:45], 3, v234
	s_and_b64 s[46:47], s[48:49], s[46:47]
	v_cmp_gt_i32_e64 s[42:43], 2, v234
	s_and_b64 s[44:45], s[46:47], s[44:45]
	v_cmp_gt_i32_e64 s[40:41], 1, v234
	s_and_b64 s[42:43], s[44:45], s[42:43]
	v_cmp_gt_i32_e64 s[38:39], 0, v234
	s_and_b64 s[40:41], s[42:43], s[40:41]
	s_and_b64 s[38:39], s[40:41], s[38:39]
	v_cmp_gt_i32_e64 s[34:35], 58, v234
	v_cndmask_b32_e64 v162, v162, v215, s[38:39]
	v_cmp_gt_i32_e64 s[38:39], 59, v234
	v_cmp_gt_i32_e64 s[30:31], 57, v234
	s_and_b64 s[34:35], s[38:39], s[34:35]
	v_cmp_gt_i32_e64 s[28:29], 56, v234
	s_and_b64 s[30:31], s[34:35], s[30:31]
	v_cmp_gt_i32_e64 s[26:27], 51, v234
	s_and_b64 s[28:29], s[30:31], s[28:29]
	v_cmp_gt_i32_e64 s[24:25], 50, v234
	s_and_b64 s[26:27], s[28:29], s[26:27]
	v_cmp_gt_i32_e64 s[22:23], 49, v234
	s_and_b64 s[24:25], s[26:27], s[24:25]
	v_cmp_gt_i32_e64 s[20:21], 48, v234
	s_and_b64 s[22:23], s[24:25], s[22:23]
	v_cmp_gt_i32_e64 s[18:19], 43, v234
	s_and_b64 s[20:21], s[22:23], s[20:21]
	v_cmp_gt_i32_e64 s[16:17], 42, v234
	s_and_b64 s[18:19], s[20:21], s[18:19]
	v_cmp_gt_i32_e64 s[14:15], 41, v234
	s_and_b64 s[16:17], s[18:19], s[16:17]
	v_cmp_gt_i32_e64 s[12:13], 40, v234
	s_and_b64 s[14:15], s[16:17], s[14:15]
	v_cmp_gt_i32_e64 s[10:11], 35, v234
	s_and_b64 s[12:13], s[14:15], s[12:13]
	v_cmp_gt_i32_e64 s[8:9], 34, v234
	s_and_b64 s[10:11], s[12:13], s[10:11]
	v_cmp_gt_i32_e64 s[6:7], 33, v234
	s_and_b64 s[8:9], s[10:11], s[8:9]
	v_cmp_gt_i32_e32 vcc, 32, v234
	s_and_b64 s[6:7], s[8:9], s[6:7]
	s_and_b64 vcc, s[6:7], vcc
	v_cndmask_b32_e64 v177, v177, v215, s[68:69]
	v_cndmask_b32_e64 v176, v176, v215, s[66:67]
	v_cndmask_b32_e64 v175, v175, v215, s[64:65]
	v_cndmask_b32_e64 v174, v174, v215, s[62:63]
	v_cndmask_b32_e64 v173, v173, v215, s[60:61]
	v_cndmask_b32_e64 v172, v172, v215, s[58:59]
	v_cndmask_b32_e64 v171, v171, v215, s[56:57]
	v_cndmask_b32_e64 v170, v170, v215, s[54:55]
	v_cndmask_b32_e64 v169, v169, v215, s[52:53]
	v_cndmask_b32_e64 v168, v168, v215, s[50:51]
	v_cndmask_b32_e64 v167, v167, v215, s[48:49]
	v_cndmask_b32_e64 v166, v166, v215, s[46:47]
	v_cndmask_b32_e64 v165, v165, v215, s[44:45]
	v_cndmask_b32_e64 v164, v164, v215, s[42:43]
	v_cndmask_b32_e64 v163, v163, v215, s[40:41]
	v_cndmask_b32_e64 v161, v161, v215, s[38:39]
	v_cndmask_b32_e64 v160, v160, v215, s[34:35]
	v_cndmask_b32_e64 v159, v159, v215, s[30:31]
	v_cndmask_b32_e64 v158, v158, v215, s[28:29]
	v_cndmask_b32_e64 v157, v157, v215, s[26:27]
	v_cndmask_b32_e64 v156, v156, v215, s[24:25]
	v_cndmask_b32_e64 v155, v155, v215, s[22:23]
	v_cndmask_b32_e64 v154, v154, v215, s[20:21]
	v_cndmask_b32_e64 v153, v153, v215, s[18:19]
	v_cndmask_b32_e64 v152, v152, v215, s[16:17]
	v_cndmask_b32_e64 v151, v151, v215, s[14:15]
	v_cndmask_b32_e64 v150, v150, v215, s[12:13]
	v_cndmask_b32_e64 v149, v149, v215, s[10:11]
	v_cndmask_b32_e64 v148, v148, v215, s[8:9]
	v_cndmask_b32_e64 v147, v147, v215, s[6:7]
	v_cndmask_b32_e32 v146, v146, v215, vcc

.Lp7dma_skip1:
	s_cmp_ge_u32 s71, s95
	s_cbranch_scc1 .LBB0_752
	s_ashr_i32 s7, s88, 2
	s_and_b32 s8, s1, 0xc000
	s_mul_hi_i32 s9, s7, 0x180000
	s_mul_i32 s7, s7, 0x180000
	s_or_b32 s8, s7, s8
	s_lshl_b64 s[8:9], s[8:9], 1
	s_add_u32 s10, s89, s8
	s_addc_u32 s11, s90, s9
	s_add_u32 s12, s74, s8
	s_addc_u32 s13, s75, s9
	s_add_u32 s8, s91, s8
	s_addc_u32 s9, s94, s9
	s_sub_i32 s7, s70, s6
	s_mov_b32 s14, m0
	s_mov_b32 m0, s7
	s_nop 0
	global_load_lds_dwordx4 v243, s[10:11]
	s_add_u32 m0, m0, 0x2000
	s_nop 0
	global_load_lds_dwordx4 v244, s[10:11]
	s_add_u32 m0, m0, 0x2000
	s_nop 0
	global_load_lds_dwordx4 v243, s[12:13]
	s_add_u32 m0, m0, 0x2000
	s_nop 0
	global_load_lds_dwordx4 v244, s[12:13]
	s_add_u32 m0, m0, 0x2000
	s_nop 0
	global_load_lds_dwordx4 v245, s[8:9]
	s_add_u32 m0, m0, 0x2000
	s_nop 0
	global_load_lds_dwordx4 v246, s[8:9]
	s_add_u32 m0, m0, 0x2000
	s_nop 0
	global_load_lds_dwordx4 v247, s[8:9]
	s_add_u32 m0, m0, 0x2000
	s_nop 0
	global_load_lds_dwordx4 v248, s[8:9]
	s_mov_b32 m0, s14
	s_branch .LBB0_752
